# v28 + lever 4: one static s_setprio 1 for waves 0-3 before the LRU item loops and the attention loop (reset at the grid barrier)
# baseline (speedup 1.0000x reference)
; template <int PASS>
; __device__ void lru_items(const Params& p, unsigned char* shm, int l) {
;     bf16_t* xraw = (bf16_t*)shm;
;     float* xcf = (float*)(shm + 8704);
;     bf16_t* xcb = (bf16_t*)(shm + 25344);
;     bf16_t* wt = (bf16_t*)(shm + 34560);
;     float* As = (float*)(shm + 71424);
;     float* Bs = (float*)(shm + 104192);
;     float* Pq = (float*)(shm + 136960);
;     float* Hq = (float*)(shm + 139008);
;     const bf16_t* XL = (const bf16_t*)(p.ws + B_XL); bf16_t* GL = (bf16_t*)(p.ws + B_GL); const bf16_t* LWT = (const bf16_t*)(p.ws + SM_LWT);
;     float* SA = (float*)(p.ws + SM_SA); float* SH = (float*)(p.ws + SM_SH); const float* CIN = (const float*)(p.ws + SM_CIN);
;     const float* cw = p.in[4] + l * 4096; const float* cbias = p.in[5] + l * 1024;
;     const int tid = ltid(p.wave), lane = tid & 63, w = tid >> 6, fr = lane & 15, fq = lane >> 4, G_ = gridDim.x, total = NCHK * 16;
;     int n_loaded = -1;
;     float c0 = 0.f, c1 = 0.f, c2 = 0.f, c3 = 0.f, cb = 0.f, gba[4], gbx[4], gsp[4];
; #pragma unroll
;     for (int jt = 0; jt < 4; ++jt) { gba[jt] = 0.f; gbx[jt] = 0.f; gsp[jt] = 0.f; }
;     u32x4 xr0 = (u32x4){0u, 0u, 0u, 0u}, xr1 = (u32x4){0u, 0u, 0u, 0u};
;     ...
;     int it = lbid();
;     if (it < total) LRU_LOAD(it);
;     for (; it < total; it += G_) {
;         const int ck = it >> 4, n = it & 15, t0 = ck * 64;
;         *(u32x4*)(xraw + (tid >> 3) * 64 + (tid & 7) * 8) = xr0;
;         if (tid < 24) *(u32x4*)(xraw + (64 + (tid >> 3)) * 64 + (tid & 7) * 8) = xr1;
;         if (n != n_loaded) {
;             n_loaded = n;
; #pragma unroll
;             for (int i = 0; i < 4; ++i) { const int e = tid + 512 * i, mtx = e >> 9, rem = e & 511, j = rem >> 3, c8 = rem & 7;
;                 *(u32x4*)(wt + (mtx * 64 + j) * 72 + c8 * 8) = *(const u32x4*)(LWT + ((size_t)(mtx * 16 + n) * 64 + j) * 64 + c8 * 8); }
;             { const int ch = n * 64 + (tid & 63); c0 = cw[ch]; c1 = cw[1024 + ch]; c2 = cw[2048 + ch]; c3 = cw[3072 + ch]; cb = cbias[ch]; }
; #pragma unroll
;             for (int jt = 0; jt < 4; ++jt) { const int pi = (l * 2 + (w >> 2)) * 1024 + n * 64 + jt * 16 + fr; gba[jt] = p.in[7][pi]; gbx[jt] = p.in[9][pi]; gsp[jt] = -8.0f * log1pf(__expf(-p.in[10][pi])); }
;         }
;         u32x4 glv = (u32x4){0u, 0u, 0u, 0u}; float cin = 0.f;
;         const size_t go = (size_t)(t0 + (tid >> 3)) * 1024 + n * 64 + (tid & 7) * 8;
.LBB0_198:
	s_or_b64 exec, exec, s[0:1]
	v_readlane_b32 s0, v254, 43
	v_readlane_b32 s1, v254, 44
	s_mov_b32 s6, s0
	s_lshl_b32 s0, s0, 12
	s_ashr_i32 s1, s0, 31
	s_lshl_b32 s4, s6, 10
	v_readlane_b32 s60, v251, 20
	s_ashr_i32 s5, s4, 31
	s_lshl_b64 s[0:1], s[0:1], 2
	v_readlane_b32 s68, v251, 28
	v_readlane_b32 s61, v251, 21
	v_readlane_b32 s69, v251, 29
	s_add_u32 s60, s68, s0
	v_readlane_b32 s62, v251, 22
	v_readlane_b32 s70, v251, 30
	s_addc_u32 s61, s69, s1
	s_lshl_b64 s[0:1], s[4:5], 2
	v_readlane_b32 s63, v251, 23
	v_readlane_b32 s71, v251, 31
	s_add_u32 s62, s70, s0
	s_addc_u32 s63, s71, s1
	v_lshlrev_b32_e32 v0, 3, v142
	v_bfe_u32 v17, v142, 3, 6
	v_readlane_b32 s0, v252, 11
	v_and_b32_e32 v26, 56, v0
	v_lshlrev_b32_e32 v0, 7, v17
	v_readlane_b32 s1, v252, 12
	v_lshlrev_b32_e32 v10, 1, v26
	v_mov_b32_e32 v11, v1
	v_lshl_add_u64 v[12:13], s[0:1], 0, v[0:1]
	v_add_u32_e32 v16, 0, v10
	v_lshl_add_u64 v[28:29], v[12:13], 0, v[10:11]
	v_lshlrev_b32_e32 v10, 2, v142
	v_and_b32_e32 v0, 0xfffffc00, v10
	v_and_b32_e32 v43, 63, v142
	v_and_b32_e32 v14, 15, v142
	v_lshl_add_u32 v0, s6, 11, v0
	v_readlane_b32 s0, v252, 15
	v_lshlrev_b32_e32 v25, 8, v27
	v_lshlrev_b32_e32 v32, 2, v26
	v_readlane_b32 s4, v254, 6
	v_add_u32_e32 v33, 0x200, v142
	v_add_u32_e32 v34, 0x400, v142
	v_add_u32_e32 v35, 0x600, v142
	v_or_b32_e32 v45, v0, v14
	v_lshlrev_b32_e32 v0, 2, v43
	v_readlane_b32 s1, v252, 16
	v_add3_u32 v50, s4, v25, v32
	v_ashrrev_i32_e32 v32, 9, v142
	v_ashrrev_i32_e32 v33, 9, v33
	v_ashrrev_i32_e32 v34, 9, v34
	v_ashrrev_i32_e32 v35, 9, v35
	v_lshl_add_u64 v[30:31], s[0:1], 0, v[0:1]
	v_lshlrev_b32_e32 v0, 1, v43
	v_lshlrev_b32_e32 v52, 4, v32
	v_lshl_or_b32 v32, v32, 6, v17
	v_lshlrev_b32_e32 v53, 4, v33
	v_lshl_or_b32 v33, v33, 6, v17
	v_lshlrev_b32_e32 v54, 4, v34
	v_lshl_or_b32 v34, v34, 6, v17
	v_lshlrev_b32_e32 v55, 4, v35
	v_lshl_or_b32 v17, v35, 6, v17
	v_lshlrev_b32_e32 v35, 1, v142
	v_ashrrev_i32_e32 v15, 6, v142
	v_add_u32_e32 v11, 0, v0
	s_movk_i32 s0, 0x90
	v_and_b32_e32 v35, 0xffffff80, v35
	s_movk_i32 s6, 0x104
	v_and_b32_e32 v46, 1, v15
	v_lshlrev_b32_e32 v18, 4, v15
	v_add_u32_e32 v56, v11, v35
	v_add3_u32 v57, 0, v35, v0
	v_mul_lo_u32 v35, v15, s6
	v_mul_lo_u32 v36, v15, s0
	v_lshlrev_b32_e32 v15, 7, v15
	v_add_u32_e32 v37, 0x400, v15
	v_add_u32_e32 v58, v11, v37
	v_add3_u32 v59, 0, v37, v0
	v_add_u32_e32 v37, 0x800, v15
	v_add_u32_e32 v60, v11, v37
	v_add3_u32 v61, 0, v37, v0
	v_add_u32_e32 v37, 0xc00, v15
	v_and_b32_e32 v18, 48, v18
	v_and_b32_e32 v20, 48, v142
	v_add_u32_e32 v62, v11, v37
	v_add3_u32 v63, 0, v37, v0
	v_add_u32_e32 v37, 0x1000, v15
	v_ashrrev_i32_e32 v13, 8, v142
	v_or_b32_e32 v19, v18, v14
	v_add_u32_e32 v21, 0, v20
	v_add_u32_e32 v64, v11, v37
	v_add3_u32 v65, 0, v37, v0
	v_add_u32_e32 v37, 0x1400, v15
	v_mad_u32_u24 v47, v19, s0, v21
	v_lshl_or_b32 v19, v13, 7, v14
	v_lshrrev_b32_e32 v22, 2, v142
	v_add_u32_e32 v66, v11, v37
	v_add3_u32 v67, 0, v37, v0
	v_add_u32_e32 v37, 0x1800, v15
	v_add_u32_e32 v15, 0x1c00, v15
	v_add_u32_e32 v12, v11, v0
	v_and_or_b32 v18, v22, 12, v18
	v_lshlrev_b32_e32 v13, 12, v13
	v_add3_u32 v69, 0, v37, v0
	v_add3_u32 v71, 0, v15, v0
	v_mul_lo_u32 v0, v19, s0
	v_add_u32_e32 v72, v21, v0
	v_add3_u32 v73, 0, v0, v20
	v_lshl_or_b32 v0, v18, 6, v13
	v_or_b32_e32 v13, v0, v14
	v_readlane_b32 s5, v254, 7
	v_lshlrev_b32_e32 v13, 2, v13
	v_add_u32_e32 v75, s4, v13
	v_add_u32_e32 v74, s5, v13
	v_or_b32_e32 v13, 64, v0
	v_or_b32_e32 v19, v13, v14
	v_lshlrev_b32_e32 v19, 2, v19
	v_add_u32_e32 v76, s5, v19
	v_add_u32_e32 v77, s4, v19
	v_or_b32_e32 v19, 0x80, v0
	v_or_b32_e32 v20, v19, v14
	v_lshlrev_b32_e32 v20, 2, v20
	v_add_u32_e32 v78, s5, v20
	v_add_u32_e32 v79, s4, v20
	v_or_b32_e32 v20, 0xc0, v0
	v_or_b32_e32 v21, v20, v14
	v_lshlrev_b32_e32 v21, 2, v21
	v_add_u32_e32 v80, s5, v21
	v_add_u32_e32 v81, s4, v21
	v_or_b32_e32 v21, 16, v14
	v_add_u32_e32 v68, v11, v37
	v_or_b32_e32 v37, v0, v21
	v_lshlrev_b32_e32 v37, 2, v37
	v_add_u32_e32 v82, s5, v37
	v_add_u32_e32 v83, s4, v37
	v_or_b32_e32 v37, v13, v21
	v_lshlrev_b32_e32 v37, 2, v37
	v_add_u32_e32 v84, s5, v37
	v_add_u32_e32 v85, s4, v37
	v_or_b32_e32 v37, v19, v21
	v_or_b32_e32 v21, v20, v21
	v_lshlrev_b32_e32 v21, 2, v21
	v_add_u32_e32 v70, v11, v15
	v_lshl_add_u32 v15, v14, 2, 0
	v_lshlrev_b32_e32 v37, 2, v37
	v_add_u32_e32 v88, s5, v21
	v_add_u32_e32 v89, s4, v21
	v_or_b32_e32 v21, 32, v14
	v_or_b32_e32 v14, 48, v14
	v_add_u32_e32 v86, s5, v37
	v_add_u32_e32 v87, s4, v37
	v_or_b32_e32 v37, v0, v21
	v_or_b32_e32 v0, v0, v14
	v_lshlrev_b32_e32 v0, 2, v0
	v_add_u32_e32 v98, s5, v0
	v_add_u32_e32 v99, s4, v0
	v_or_b32_e32 v0, v13, v14
	v_lshlrev_b32_e32 v0, 2, v0
	v_add_u32_e32 v100, s5, v0
	v_add_u32_e32 v101, s4, v0
	v_or_b32_e32 v0, v19, v14
	v_lshlrev_b32_e32 v0, 2, v0
	v_ashrrev_i32_e32 v22, 7, v142
	v_add_u32_e32 v102, s5, v0
	v_add_u32_e32 v103, s4, v0
	v_or_b32_e32 v0, v20, v14
	v_lshlrev_b32_e32 v23, 4, v22
	v_lshlrev_b32_e32 v0, 2, v0
	v_lshlrev_b32_e32 v37, 2, v37
	v_add_u32_e32 v104, s5, v0
	v_add_u32_e32 v105, s4, v0
	v_or_b32_e32 v0, 1, v23
	v_cmp_eq_u32_e32 vcc, 0, v46
	v_add_u32_e32 v90, s5, v37
	v_add_u32_e32 v91, s4, v37
	v_or_b32_e32 v37, v13, v21
	v_sub_u32_e32 v13, 63, v0
	v_cndmask_b32_e32 v0, v13, v0, vcc
; __device__ __forceinline__ int ltid(int wave) { int t = (wave << 6) | (int)__builtin_amdgcn_mbcnt_hi(~0u, __builtin_amdgcn_mbcnt_lo(~0u, 0u)); asm volatile("" : "+v"(t)); return t; }
; __device__ __forceinline__ int lbid() { int b = blockIdx.x; asm volatile("" : "+s"(b)); return b; }
; template <int PASS>
; __device__ void lru_items(const Params& p, unsigned char* shm, int l) {
;     ...
;     const int tid = ltid(p.wave), lane = tid & 63, w = tid >> 6, fr = lane & 15, fq = lane >> 4, G_ = gridDim.x, total = NCHK * 16;
;     int n_loaded = -1;
;     float c0 = 0.f, c1 = 0.f, c2 = 0.f, c3 = 0.f, cb = 0.f, gba[4], gbx[4], gsp[4];
; #pragma unroll
;     for (int jt = 0; jt < 4; ++jt) { gba[jt] = 0.f; gbx[jt] = 0.f; gsp[jt] = 0.f; }
;     u32x4 xr0 = (u32x4){0u, 0u, 0u, 0u}, xr1 = (u32x4){0u, 0u, 0u, 0u};
;     ...
;     int it = lbid();
;     if (it < total) LRU_LOAD(it);
;     for (; it < total; it += G_) {
;     ...
;             const int seg = tid >> 7, d = (tid >> 6) & 1, j = tid & 63;
;             float h = 0.f, P = 1.f;
; #pragma unroll
;             for (int s = 0; s < 16; ++s) { const int st = seg * 16 + s, t = d ? 63 - st : st; const float a = As[(d * 64 + t) * 64 + j]; h = a * h + Bs[(d * 64 + t) * 64 + j]; P *= a; }
;             Pq[seg * 128 + (tid & 127)] = P; Hq[seg * 128 + (tid & 127)] = h;
;             __syncthreads();
;             if (PASS == 0) {
;                 if (tid < 128) { float hh = Hq[tid], PP = Pq[tid];
; #pragma unroll
;                     for (int q = 1; q < 4; ++q) { const float pq = Pq[q * 128 + tid]; hh = pq * hh + Hq[q * 128 + tid]; PP *= pq; }
;                     SA[so] = PP; SH[so] = hh; }
;             } else {
;                 float c = cin;
; #pragma unroll
;                 for (int q = 0; q < 3; ++q) if (q < seg) c = Pq[q * 128 + (tid & 127)] * c + Hq[q * 128 + (tid & 127)];
; #pragma unroll
;                 for (int s = 0; s < 16; ++s) { const int st = seg * 16 + s, t = d ? 63 - st : st; c = As[(d * 64 + t) * 64 + j] * c + Bs[(d * 64 + t) * 64 + j]; Bs[(d * 64 + t) * 64 + j] = c; }
	v_lshl_or_b32 v24, v46, 12, v43
	v_lshlrev_b32_e32 v0, 6, v0
	v_add_lshl_u32 v0, v0, v24, 2
	v_add_u32_e32 v107, s5, v0
	v_add_u32_e32 v108, s4, v0
	v_or_b32_e32 v0, 2, v23
	v_sub_u32_e32 v13, 63, v0
	v_cndmask_b32_e32 v0, v13, v0, vcc
	v_lshlrev_b32_e32 v0, 6, v0
	v_add_lshl_u32 v0, v0, v24, 2
	v_add_u32_e32 v109, s5, v0
	v_add_u32_e32 v110, s4, v0
	v_or_b32_e32 v0, 3, v23
	v_sub_u32_e32 v13, 63, v0
	v_cndmask_b32_e32 v0, v13, v0, vcc
	v_lshlrev_b32_e32 v0, 6, v0
	v_add_lshl_u32 v0, v0, v24, 2
	v_add_u32_e32 v111, s5, v0
	v_add_u32_e32 v112, s4, v0
	v_or_b32_e32 v0, 4, v23
	v_sub_u32_e32 v13, 63, v0
	v_cndmask_b32_e32 v0, v13, v0, vcc
	v_lshlrev_b32_e32 v0, 6, v0
	v_add_lshl_u32 v0, v0, v24, 2
	v_add_u32_e32 v113, s5, v0
	v_add_u32_e32 v114, s4, v0
	v_or_b32_e32 v0, 5, v23
	v_sub_u32_e32 v13, 63, v0
	v_cndmask_b32_e32 v0, v13, v0, vcc
	v_lshlrev_b32_e32 v0, 6, v0
	v_add_lshl_u32 v0, v0, v24, 2
	v_add_u32_e32 v115, s5, v0
	v_add_u32_e32 v116, s4, v0
	v_or_b32_e32 v0, 6, v23
	v_sub_u32_e32 v13, 63, v0
	v_cndmask_b32_e32 v0, v13, v0, vcc
	v_lshlrev_b32_e32 v0, 6, v0
	v_add_lshl_u32 v0, v0, v24, 2
	v_add_u32_e32 v117, s5, v0
	v_add_u32_e32 v118, s4, v0
	v_or_b32_e32 v0, 7, v23
	v_sub_u32_e32 v13, 63, v0
	v_cndmask_b32_e32 v0, v13, v0, vcc
	v_lshlrev_b32_e32 v0, 6, v0
	v_add_lshl_u32 v0, v0, v24, 2
	v_add_u32_e32 v119, s5, v0
	v_add_u32_e32 v120, s4, v0
	v_or_b32_e32 v0, 8, v23
	v_sub_u32_e32 v13, 63, v0
	v_cndmask_b32_e32 v0, v13, v0, vcc
	v_lshlrev_b32_e32 v0, 6, v0
	v_add_lshl_u32 v0, v0, v24, 2
	v_add_u32_e32 v121, s5, v0
	v_add_u32_e32 v122, s4, v0
	v_or_b32_e32 v0, 9, v23
	v_sub_u32_e32 v13, 63, v0
	v_cndmask_b32_e32 v0, v13, v0, vcc
	v_lshlrev_b32_e32 v0, 6, v0
	v_add_lshl_u32 v0, v0, v24, 2
	v_add_u32_e32 v123, s5, v0
	v_add_u32_e32 v124, s4, v0
	v_or_b32_e32 v0, 10, v23
	v_sub_u32_e32 v13, 63, v0
	v_cndmask_b32_e32 v0, v13, v0, vcc
	v_lshlrev_b32_e32 v0, 6, v0
	v_add_lshl_u32 v0, v0, v24, 2
	v_add_u32_e32 v125, s5, v0
	v_add_u32_e32 v126, s4, v0
	v_or_b32_e32 v0, 11, v23
	v_sub_u32_e32 v13, 63, v0
	v_cndmask_b32_e32 v0, v13, v0, vcc
	v_lshlrev_b32_e32 v0, 6, v0
	v_add_lshl_u32 v0, v0, v24, 2
	v_add_u32_e32 v127, s5, v0
	v_add_u32_e32 v128, s4, v0
	v_or_b32_e32 v0, 12, v23
	v_sub_u32_e32 v13, 63, v0
	v_cndmask_b32_e32 v0, v13, v0, vcc
	v_lshlrev_b32_e32 v0, 6, v0
	v_add_lshl_u32 v0, v0, v24, 2
	v_add_u32_e32 v129, s5, v0
	v_add_u32_e32 v130, s4, v0
	v_or_b32_e32 v0, 13, v23
	v_sub_u32_e32 v13, 63, v0
	v_cndmask_b32_e32 v0, v13, v0, vcc
	v_lshlrev_b32_e32 v0, 6, v0
	v_add_lshl_u32 v0, v0, v24, 2
	v_add_u32_e32 v131, s5, v0
	v_add_u32_e32 v132, s4, v0
	v_or_b32_e32 v0, 14, v23
	v_sub_u32_e32 v13, 63, v0
	v_cndmask_b32_e32 v0, v13, v0, vcc
	v_lshlrev_b32_e32 v0, 6, v0
	v_add_lshl_u32 v0, v0, v24, 2
	v_add_u32_e32 v133, s5, v0
	v_add_u32_e32 v134, s4, v0
	v_or_b32_e32 v0, 15, v23
	v_sub_u32_e32 v13, 63, v0
	v_cndmask_b32_e32 v0, v13, v0, vcc
	v_lshlrev_b32_e32 v0, 6, v0
	v_add_lshl_u32 v0, v0, v24, 2
	v_readlane_b32 s1, v254, 4
	v_readlane_b32 s3, v254, 5
	v_sub_u32_e32 v25, 63, v23
	v_add_u32_e32 v135, s5, v0
	v_add_u32_e32 v136, s4, v0
	v_and_b32_e32 v0, 0x1fc, v10
	v_add_u32_e32 v48, s1, v10
	v_add_u32_e32 v49, s3, v10
	v_cndmask_b32_e32 v25, v25, v23, vcc
	v_lshlrev_b32_e32 v37, 2, v37
	v_add_u32_e32 v137, s3, v0
	v_add_u32_e32 v138, s1, v0
	v_or_b32_e32 v10, 0x200, v0
	v_or_b32_e32 v0, 0x400, v0
	v_lshlrev_b32_e32 v25, 6, v25
	v_mul_lo_u32 v32, v32, s0
	v_mul_lo_u32 v33, v33, s0
	v_mul_lo_u32 v34, v34, s0
	v_mul_lo_u32 v17, v17, s0
	v_add_u32_e32 v92, s5, v37
	v_add_u32_e32 v93, s4, v37
	v_or_b32_e32 v37, v19, v21
	v_or_b32_e32 v21, v20, v21
	v_add_u32_e32 v140, s1, v10
	v_add_u32_e32 v142, s1, v0
	v_readlane_b32 s0, v251, 10
	v_add_lshl_u32 v25, v25, v24, 2
	v_mul_u32_u24_e32 v18, 0x104, v18
	v_lshlrev_b32_e32 v37, 2, v37
	v_lshlrev_b32_e32 v21, 2, v21
	v_add_u32_e32 v141, s3, v0
	s_add_i32 s0, s0, s2
	v_mov_b32_e32 v0, v1
	v_lshl_add_u32 v44, v27, 7, v16
	v_add_u32_e32 v51, s5, v25
	v_add_u32_e32 v94, s5, v37
	v_add_u32_e32 v95, s4, v37
	v_add_u32_e32 v96, s5, v21
	v_add_u32_e32 v97, s4, v21
	v_add_u32_e32 v106, s4, v25
	v_cmp_lt_i32_e64 s[38:39], 0, v22
	v_cmp_lt_i32_e64 s[40:41], 1, v22
	v_add_u32_e32 v139, s3, v10
	v_cmp_lt_i32_e64 s[42:43], 2, v22
	s_lshl_b32 s3, s0, 2
	s_mov_b32 s5, -1
	v_add_u32_e32 v143, v16, v32
	v_add_u32_e32 v144, v16, v33
	v_add_u32_e32 v145, v16, v34
	v_add_u32_e32 v146, v16, v17
	v_add_u32_e32 v147, v12, v35
	v_add_u32_e32 v148, v11, v36
	v_add_u32_e32 v149, v15, v18
	v_mov_b32_e32 v160, 0
	v_mov_b32_e32 v161, 0
	v_mov_b32_e32 v162, 0
	v_mov_b32_e32 v163, 0
	v_mov_b64_e32 v[34:35], v[0:1]
	v_mov_b64_e32 v[36:37], v[0:1]
	v_mov_b32_e32 v164, 0
	v_mov_b32_e32 v165, 0
	v_mov_b32_e32 v166, 0
	v_mov_b32_e32 v167, 0
	v_mov_b32_e32 v168, 0
	v_mov_b32_e32 v169, 0
	v_mov_b32_e32 v170, 0
	v_mov_b32_e32 v171, 0
	v_readlane_b32 s64, v251, 24
	v_readlane_b32 s65, v251, 25
	v_readlane_b32 s66, v251, 26
	v_readlane_b32 s67, v251, 27
	v_readlane_b32 s72, v251, 32
	v_readlane_b32 s73, v251, 33
	v_readlane_b32 s74, v251, 34
	v_readlane_b32 s75, v251, 35
	v_readlane_b32 s1, v251, 11
	s_waitcnt vmcnt(0)
	v_readfirstlane_b32 s0, v229
	s_lshr_b32 s0, s0, 6
	s_cmp_ge_u32 s0, 4
	s_cbranch_scc1 .Lprio_skip1
	s_setprio 1

; template <int PASS>
; __device__ void lru_items(const Params& p, unsigned char* shm, int l) {
;     bf16_t* xraw = (bf16_t*)shm;
;     float* xcf = (float*)(shm + 8704);
;     bf16_t* xcb = (bf16_t*)(shm + 25344);
;     bf16_t* wt = (bf16_t*)(shm + 34560);
;     float* As = (float*)(shm + 71424);
;     float* Bs = (float*)(shm + 104192);
;     float* Pq = (float*)(shm + 136960);
;     float* Hq = (float*)(shm + 139008);
;     const bf16_t* XL = (const bf16_t*)(p.ws + B_XL); bf16_t* GL = (bf16_t*)(p.ws + B_GL); const bf16_t* LWT = (const bf16_t*)(p.ws + SM_LWT);
;     float* SA = (float*)(p.ws + SM_SA); float* SH = (float*)(p.ws + SM_SH); const float* CIN = (const float*)(p.ws + SM_CIN);
;     const float* cw = p.in[4] + l * 4096; const float* cbias = p.in[5] + l * 1024;
;     const int tid = ltid(p.wave), lane = tid & 63, w = tid >> 6, fr = lane & 15, fq = lane >> 4, G_ = gridDim.x, total = NCHK * 16;
;     int n_loaded = -1;
;     float c0 = 0.f, c1 = 0.f, c2 = 0.f, c3 = 0.f, cb = 0.f, gba[4], gbx[4], gsp[4];
; #pragma unroll
;     for (int jt = 0; jt < 4; ++jt) { gba[jt] = 0.f; gbx[jt] = 0.f; gsp[jt] = 0.f; }
;     u32x4 xr0 = (u32x4){0u, 0u, 0u, 0u}, xr1 = (u32x4){0u, 0u, 0u, 0u};
;     ...
;     int it = lbid();
;     if (it < total) LRU_LOAD(it);
;     for (; it < total; it += G_) {
;         const int ck = it >> 4, n = it & 15, t0 = ck * 64;
;         *(u32x4*)(xraw + (tid >> 3) * 64 + (tid & 7) * 8) = xr0;
;         if (tid < 24) *(u32x4*)(xraw + (64 + (tid >> 3)) * 64 + (tid & 7) * 8) = xr1;
;         if (n != n_loaded) {
;             n_loaded = n;
; #pragma unroll
;             for (int i = 0; i < 4; ++i) { const int e = tid + 512 * i, mtx = e >> 9, rem = e & 511, j = rem >> 3, c8 = rem & 7;
;                 *(u32x4*)(wt + (mtx * 64 + j) * 72 + c8 * 8) = *(const u32x4*)(LWT + ((size_t)(mtx * 16 + n) * 64 + j) * 64 + c8 * 8); }
;             { const int ch = n * 64 + (tid & 63); c0 = cw[ch]; c1 = cw[1024 + ch]; c2 = cw[2048 + ch]; c3 = cw[3072 + ch]; cb = cbias[ch]; }
; #pragma unroll
;             for (int jt = 0; jt < 4; ++jt) { const int pi = (l * 2 + (w >> 2)) * 1024 + n * 64 + jt * 16 + fr; gba[jt] = p.in[7][pi]; gbx[jt] = p.in[9][pi]; gsp[jt] = -8.0f * log1pf(__expf(-p.in[10][pi])); }
;         }
;         u32x4 glv = (u32x4){0u, 0u, 0u, 0u}; float cin = 0.f;
;         const size_t go = (size_t)(t0 + (tid >> 3)) * 1024 + n * 64 + (tid & 7) * 8;
.LBB0_294:
	s_or_b64 exec, exec, s[0:1]
	v_readlane_b32 s0, v254, 43
	v_readlane_b32 s1, v254, 44
	s_mov_b32 s6, s0
	s_lshl_b32 s0, s0, 12
	s_ashr_i32 s1, s0, 31
	s_lshl_b32 s4, s6, 10
	v_readlane_b32 s60, v251, 20
	s_ashr_i32 s5, s4, 31
	s_lshl_b64 s[0:1], s[0:1], 2
	v_readlane_b32 s68, v251, 28
	v_readlane_b32 s69, v251, 29
	s_add_u32 s42, s68, s0
	v_readlane_b32 s70, v251, 30
	s_addc_u32 s43, s69, s1
	s_lshl_b64 s[0:1], s[4:5], 2
	v_readlane_b32 s71, v251, 31
	s_add_u32 s46, s70, s0
	s_addc_u32 s47, s71, s1
	v_lshlrev_b32_e32 v0, 3, v13
	v_bfe_u32 v19, v13, 3, 6
	v_readlane_b32 s0, v252, 11
	v_and_b32_e32 v28, 56, v0
	v_lshlrev_b32_e32 v0, 7, v19
	v_readlane_b32 s1, v252, 12
	v_lshlrev_b32_e32 v10, 1, v28
	v_mov_b32_e32 v11, v1
	v_lshl_add_u64 v[14:15], s[0:1], 0, v[0:1]
	v_lshlrev_b32_e32 v0, 2, v13
	v_add_u32_e32 v18, 0, v10
	v_lshl_add_u64 v[30:31], v[14:15], 0, v[10:11]
	v_and_b32_e32 v10, 0xfffffc00, v0
	v_and_b32_e32 v26, 63, v13
	v_and_b32_e32 v16, 15, v13
	v_lshl_add_u32 v10, s6, 11, v10
	s_movk_i32 s0, 0x80
	v_ashrrev_i32_e32 v17, 6, v13
	v_or_b32_e32 v42, v10, v16
	v_lshlrev_b32_e32 v10, 1, v26
	v_ashrrev_i32_e32 v15, 8, v13
	v_and_b32_e32 v22, 48, v13
	v_lshrrev_b32_e32 v24, 2, v13
	v_cmp_gt_i32_e64 s[38:39], s0, v13
	v_ashrrev_i32_e32 v32, 9, v13
	v_add_u32_e32 v33, 0x200, v13
	v_add_u32_e32 v34, 0x400, v13
	v_add_u32_e32 v35, 0x600, v13
	v_lshlrev_b32_e32 v13, 1, v13
	v_add_u32_e32 v11, 0, v10
	s_movk_i32 s1, 0x90
	v_ashrrev_i32_e32 v33, 9, v33
	v_ashrrev_i32_e32 v34, 9, v34
	v_ashrrev_i32_e32 v35, 9, v35
	v_and_b32_e32 v13, 0xffffff80, v13
	s_movk_i32 s0, 0x104
	v_and_b32_e32 v43, 1, v17
	v_lshlrev_b32_e32 v20, 4, v17
	v_lshlrev_b32_e32 v47, 4, v32
	v_lshl_or_b32 v32, v32, 6, v19
	v_lshlrev_b32_e32 v48, 4, v33
	v_lshl_or_b32 v33, v33, 6, v19
	v_lshlrev_b32_e32 v49, 4, v34
	v_lshl_or_b32 v34, v34, 6, v19
	v_lshlrev_b32_e32 v50, 4, v35
	v_lshl_or_b32 v19, v35, 6, v19
	v_add_u32_e32 v51, v11, v13
	v_add3_u32 v52, 0, v13, v10
	v_mul_lo_u32 v13, v17, s0
	v_mul_lo_u32 v35, v17, s1
	v_lshlrev_b32_e32 v17, 7, v17
	v_add_u32_e32 v36, 0x400, v17
	v_add_u32_e32 v53, v11, v36
	v_add3_u32 v54, 0, v36, v10
	v_add_u32_e32 v36, 0x800, v17
	v_and_b32_e32 v20, 48, v20
	v_add_u32_e32 v55, v11, v36
	v_add3_u32 v56, 0, v36, v10
	v_add_u32_e32 v36, 0xc00, v17
	v_or_b32_e32 v21, v20, v16
	v_add_u32_e32 v23, 0, v22
	v_add_u32_e32 v57, v11, v36
	v_add3_u32 v58, 0, v36, v10
	v_add_u32_e32 v36, 0x1000, v17
	v_mad_u32_u24 v44, v21, s1, v23
	v_lshl_or_b32 v21, v15, 7, v16
	v_and_or_b32 v20, v24, 12, v20
	v_lshlrev_b32_e32 v15, 12, v15
	v_add_u32_e32 v59, v11, v36
	v_add3_u32 v60, 0, v36, v10
	v_add_u32_e32 v36, 0x1400, v17
	v_add_u32_e32 v61, v11, v36
	v_add3_u32 v62, 0, v36, v10
	v_add_u32_e32 v36, 0x1800, v17
	v_add_u32_e32 v17, 0x1c00, v17
	v_lshl_or_b32 v15, v20, 6, v15
	v_add_u32_e32 v65, v11, v17
	v_add3_u32 v66, 0, v17, v10
	v_or_b32_e32 v17, v15, v16
	v_add_u32_e32 v14, v11, v10
	v_mul_lo_u32 v32, v32, s1
	v_mul_lo_u32 v33, v33, s1
	v_mul_lo_u32 v34, v34, s1
	v_mul_lo_u32 v19, v19, s1
	v_add3_u32 v64, 0, v36, v10
	v_mul_lo_u32 v10, v21, s1
	v_lshlrev_b32_e32 v17, 2, v17
	v_readlane_b32 s1, v254, 7
	v_readlane_b32 s0, v254, 6
	v_add3_u32 v68, 0, v10, v22
	v_add_u32_e32 v69, s1, v17
	v_add_u32_e32 v70, s0, v17
	v_or_b32_e32 v17, 64, v15
	v_or_b32_e32 v21, v17, v16
	v_lshlrev_b32_e32 v21, 2, v21
	v_add_u32_e32 v71, s1, v21
	v_add_u32_e32 v72, s0, v21
	v_or_b32_e32 v21, 0x80, v15
	v_or_b32_e32 v22, v21, v16
	v_lshlrev_b32_e32 v22, 2, v22
	v_add_u32_e32 v73, s1, v22
	v_add_u32_e32 v74, s0, v22
	v_or_b32_e32 v22, 0xc0, v15
	v_add_u32_e32 v67, v23, v10
	v_or_b32_e32 v23, v22, v16
	v_lshlrev_b32_e32 v23, 2, v23
	v_add_u32_e32 v75, s1, v23
	v_add_u32_e32 v76, s0, v23
	v_or_b32_e32 v23, 16, v16
	v_add_u32_e32 v63, v11, v36
	v_or_b32_e32 v36, v15, v23
	v_lshlrev_b32_e32 v36, 2, v36
	v_add_u32_e32 v77, s1, v36
	v_add_u32_e32 v78, s0, v36
	v_or_b32_e32 v36, v17, v23
	v_lshlrev_b32_e32 v36, 2, v36
	v_add_u32_e32 v79, s1, v36
	v_add_u32_e32 v80, s0, v36
	v_or_b32_e32 v36, v21, v23
	v_or_b32_e32 v23, v22, v23
	v_lshlrev_b32_e32 v23, 2, v23
	v_lshl_add_u32 v10, v16, 2, 0
	v_lshlrev_b32_e32 v36, 2, v36
	v_add_u32_e32 v83, s1, v23
	v_add_u32_e32 v84, s0, v23
	v_or_b32_e32 v23, 32, v16
	v_or_b32_e32 v16, 48, v16
	v_add_u32_e32 v81, s1, v36
	v_add_u32_e32 v82, s0, v36
	v_or_b32_e32 v36, v15, v23
	v_or_b32_e32 v15, v15, v16
	v_lshlrev_b32_e32 v15, 2, v15
	v_add_u32_e32 v93, s1, v15
	v_add_u32_e32 v94, s0, v15
	v_or_b32_e32 v15, v17, v16
	v_lshlrev_b32_e32 v15, 2, v15
	v_add_u32_e32 v95, s1, v15
	v_add_u32_e32 v96, s0, v15
	v_or_b32_e32 v15, v21, v16
	v_lshlrev_b32_e32 v15, 2, v15
	v_add_u32_e32 v97, s1, v15
	v_add_u32_e32 v98, s0, v15
	v_or_b32_e32 v15, v22, v16
	v_and_b32_e32 v24, -16, v12
	v_lshlrev_b32_e32 v15, 2, v15
	v_add_u32_e32 v99, s1, v15
	v_add_u32_e32 v100, s0, v15
	v_sub_u32_e32 v15, 63, v24
	v_cmp_eq_u32_e32 vcc, 0, v43
	v_lshl_or_b32 v25, v43, 12, v26
	v_lshl_add_u32 v29, v12, 7, v18
	v_cndmask_b32_e32 v15, v15, v24, vcc
	v_lshlrev_b32_e32 v15, 6, v15
	v_add_lshl_u32 v15, v15, v25, 2
	v_add_u32_e32 v101, s1, v15
	v_add_u32_e32 v102, s0, v15
	v_or_b32_e32 v15, 1, v24
	v_sub_u32_e32 v16, 63, v15
; __device__ __forceinline__ int ltid(int wave) { int t = (wave << 6) | (int)__builtin_amdgcn_mbcnt_hi(~0u, __builtin_amdgcn_mbcnt_lo(~0u, 0u)); asm volatile("" : "+v"(t)); return t; }
; __device__ __forceinline__ int lbid() { int b = blockIdx.x; asm volatile("" : "+s"(b)); return b; }
; template <int PASS>
; __device__ void lru_items(const Params& p, unsigned char* shm, int l) {
;     ...
;     const int tid = ltid(p.wave), lane = tid & 63, w = tid >> 6, fr = lane & 15, fq = lane >> 4, G_ = gridDim.x, total = NCHK * 16;
;     int n_loaded = -1;
;     float c0 = 0.f, c1 = 0.f, c2 = 0.f, c3 = 0.f, cb = 0.f, gba[4], gbx[4], gsp[4];
; #pragma unroll
;     for (int jt = 0; jt < 4; ++jt) { gba[jt] = 0.f; gbx[jt] = 0.f; gsp[jt] = 0.f; }
;     u32x4 xr0 = (u32x4){0u, 0u, 0u, 0u}, xr1 = (u32x4){0u, 0u, 0u, 0u};
;     ...
;     int it = lbid();
;     if (it < total) LRU_LOAD(it);
;     ...
;             const int seg = tid >> 7, d = (tid >> 6) & 1, j = tid & 63;
;             float h = 0.f, P = 1.f;
; #pragma unroll
;             for (int s = 0; s < 16; ++s) { const int st = seg * 16 + s, t = d ? 63 - st : st; const float a = As[(d * 64 + t) * 64 + j]; h = a * h + Bs[(d * 64 + t) * 64 + j]; P *= a; }
	v_cndmask_b32_e32 v15, v16, v15, vcc
	v_lshlrev_b32_e32 v15, 6, v15
	v_add_lshl_u32 v15, v15, v25, 2
	v_add_u32_e32 v103, s1, v15
	v_add_u32_e32 v104, s0, v15
	v_or_b32_e32 v15, 2, v24
	v_sub_u32_e32 v16, 63, v15
	v_cndmask_b32_e32 v15, v16, v15, vcc
	v_lshlrev_b32_e32 v15, 6, v15
	v_add_lshl_u32 v15, v15, v25, 2
	v_add_u32_e32 v105, s1, v15
	v_add_u32_e32 v106, s0, v15
	v_or_b32_e32 v15, 3, v24
	v_sub_u32_e32 v16, 63, v15
	v_cndmask_b32_e32 v15, v16, v15, vcc
	v_lshlrev_b32_e32 v15, 6, v15
	v_add_lshl_u32 v15, v15, v25, 2
	v_add_u32_e32 v107, s1, v15
	v_add_u32_e32 v108, s0, v15
	v_or_b32_e32 v15, 4, v24
	v_sub_u32_e32 v16, 63, v15
	v_cndmask_b32_e32 v15, v16, v15, vcc
	v_lshlrev_b32_e32 v15, 6, v15
	v_add_lshl_u32 v15, v15, v25, 2
	v_add_u32_e32 v109, s1, v15
	v_add_u32_e32 v110, s0, v15
	v_or_b32_e32 v15, 5, v24
	v_sub_u32_e32 v16, 63, v15
	v_cndmask_b32_e32 v15, v16, v15, vcc
	v_lshlrev_b32_e32 v15, 6, v15
	v_add_lshl_u32 v15, v15, v25, 2
	v_add_u32_e32 v111, s1, v15
	v_add_u32_e32 v112, s0, v15
	v_or_b32_e32 v15, 6, v24
	v_sub_u32_e32 v16, 63, v15
	v_cndmask_b32_e32 v15, v16, v15, vcc
	v_lshlrev_b32_e32 v15, 6, v15
	v_add_lshl_u32 v15, v15, v25, 2
	v_add_u32_e32 v113, s1, v15
	v_add_u32_e32 v114, s0, v15
	v_or_b32_e32 v15, 7, v24
	v_sub_u32_e32 v16, 63, v15
	v_cndmask_b32_e32 v15, v16, v15, vcc
	v_lshlrev_b32_e32 v15, 6, v15
	v_add_lshl_u32 v15, v15, v25, 2
	v_add_u32_e32 v115, s1, v15
	v_add_u32_e32 v116, s0, v15
	v_or_b32_e32 v15, 8, v24
	v_sub_u32_e32 v16, 63, v15
	v_cndmask_b32_e32 v15, v16, v15, vcc
	v_lshlrev_b32_e32 v15, 6, v15
	v_add_lshl_u32 v15, v15, v25, 2
	v_add_u32_e32 v117, s1, v15
	v_add_u32_e32 v118, s0, v15
	v_or_b32_e32 v15, 9, v24
	v_sub_u32_e32 v16, 63, v15
	v_cndmask_b32_e32 v15, v16, v15, vcc
	v_lshlrev_b32_e32 v15, 6, v15
	v_add_lshl_u32 v15, v15, v25, 2
	v_add_u32_e32 v119, s1, v15
	v_add_u32_e32 v120, s0, v15
	v_or_b32_e32 v15, 10, v24
	v_sub_u32_e32 v16, 63, v15
	v_cndmask_b32_e32 v15, v16, v15, vcc
	v_lshlrev_b32_e32 v15, 6, v15
	v_add_lshl_u32 v15, v15, v25, 2
	v_add_u32_e32 v121, s1, v15
	v_add_u32_e32 v122, s0, v15
	v_or_b32_e32 v15, 11, v24
	v_sub_u32_e32 v16, 63, v15
	v_cndmask_b32_e32 v15, v16, v15, vcc
	v_lshlrev_b32_e32 v15, 6, v15
	v_add_lshl_u32 v15, v15, v25, 2
	v_add_u32_e32 v123, s1, v15
	v_add_u32_e32 v124, s0, v15
	v_or_b32_e32 v15, 12, v24
	v_sub_u32_e32 v16, 63, v15
	v_cndmask_b32_e32 v15, v16, v15, vcc
	v_lshlrev_b32_e32 v15, 6, v15
	v_add_lshl_u32 v15, v15, v25, 2
	v_add_u32_e32 v125, s1, v15
	v_add_u32_e32 v126, s0, v15
	v_or_b32_e32 v15, 13, v24
	v_sub_u32_e32 v16, 63, v15
	v_cndmask_b32_e32 v15, v16, v15, vcc
	v_lshlrev_b32_e32 v15, 6, v15
	v_add_lshl_u32 v15, v15, v25, 2
	v_add_u32_e32 v127, s1, v15
	v_add_u32_e32 v128, s0, v15
	v_or_b32_e32 v15, 14, v24
	v_sub_u32_e32 v16, 63, v15
	v_cndmask_b32_e32 v15, v16, v15, vcc
	v_lshlrev_b32_e32 v15, 6, v15
	v_add_lshl_u32 v15, v15, v25, 2
	v_or_b32_e32 v12, 15, v12
	v_lshlrev_b32_e32 v36, 2, v36
	v_add_u32_e32 v129, s1, v15
	v_add_u32_e32 v131, s0, v15
	v_sub_u32_e32 v15, 63, v12
	v_add_u32_e32 v85, s1, v36
	v_add_u32_e32 v86, s0, v36
	v_or_b32_e32 v36, v17, v23
	v_cndmask_b32_e32 v12, v15, v12, vcc
	v_lshlrev_b32_e32 v36, 2, v36
	v_lshlrev_b32_e32 v12, 6, v12
	v_add_u32_e32 v87, s1, v36
	v_add_u32_e32 v88, s0, v36
	v_or_b32_e32 v36, v21, v23
	v_or_b32_e32 v23, v22, v23
	v_add_lshl_u32 v12, v12, v25, 2
	v_readlane_b32 s3, v254, 4
	v_readlane_b32 s4, v254, 5
	v_lshlrev_b32_e32 v36, 2, v36
	v_lshlrev_b32_e32 v23, 2, v23
	v_add_u32_e32 v132, s1, v12
	v_add_u32_e32 v133, s0, v12
	v_add_u32_e32 v12, 0x200, v0
	v_add_u32_e32 v45, s3, v0
	v_add_u32_e32 v46, s4, v0
	v_add_u32_e32 v89, s1, v36
	v_add_u32_e32 v90, s0, v36
	v_add_u32_e32 v91, s1, v23
	v_add_u32_e32 v92, s0, v23
	v_add_u32_e32 v134, s3, v12
	v_add_u32_e32 v135, s4, v12
	v_add_u32_e32 v12, 0x400, v0
	v_add_u32_e32 v0, 0x600, v0
	v_readlane_b32 s0, v251, 10
	v_mul_u32_u24_e32 v20, 0x104, v20
	v_add_u32_e32 v138, s3, v0
	v_add_u32_e32 v139, s4, v0
	s_add_i32 s0, s0, s2
	v_mov_b32_e32 v0, v1
	v_add_u32_e32 v136, s3, v12
	v_add_u32_e32 v137, s4, v12
	s_lshl_b32 s3, s0, 2
	s_mov_b32 s6, -1
	v_add_u32_e32 v141, v18, v32
	v_add_u32_e32 v142, v18, v33
	v_add_u32_e32 v143, v18, v34
	v_add_u32_e32 v144, v18, v19
	v_add_u32_e32 v145, v14, v13
	v_add_u32_e32 v146, v11, v35
	v_add_u32_e32 v147, v10, v20
	v_mov_b32_e32 v154, 0
	v_mov_b32_e32 v155, 0
	v_mov_b32_e32 v156, 0
	v_mov_b32_e32 v157, 0
	v_mov_b64_e32 v[32:33], v[0:1]
	v_mov_b64_e32 v[34:35], v[0:1]
	v_mov_b32_e32 v158, 0
	v_mov_b32_e32 v159, 0
	v_mov_b32_e32 v160, 0
	v_mov_b32_e32 v161, 0
	v_mov_b32_e32 v162, 0
	v_mov_b32_e32 v163, 0
	v_mov_b32_e32 v164, 0
	v_mov_b32_e32 v165, 0
	v_readlane_b32 s61, v251, 21
	v_readlane_b32 s62, v251, 22
	v_readlane_b32 s63, v251, 23
	v_readlane_b32 s64, v251, 24
	v_readlane_b32 s65, v251, 25
	v_readlane_b32 s66, v251, 26
	v_readlane_b32 s67, v251, 27
	v_readlane_b32 s72, v251, 32
	v_readlane_b32 s73, v251, 33
	v_readlane_b32 s74, v251, 34
	v_readlane_b32 s75, v251, 35
	v_readlane_b32 s1, v251, 11
	s_waitcnt vmcnt(0)
	v_readfirstlane_b32 s0, v229
	s_lshr_b32 s0, s0, 6
	s_cmp_ge_u32 s0, 4
	s_cbranch_scc1 .Lprio_skip2
	s_setprio 1

; __device__ void attn_items(const Params& p, unsigned char* shm) {
;     ...
;     const int tid = ltid(p.wave), lane = tid & 63, w = tid >> 6, fr = lane & 15, fq = lane >> 4, G_ = gridDim.x;
;     for (int i = tid; i < 24 * 129; i += 512) { const int hd = i / 129, j = i % 129; BT[hd * 132 + j] = p.in[21][(int)BUCKET[hd >> 3][j] * 24 + hd]; }
;     u32x4 kreg[5], vreg[5]; bf16x8 q0r, q1r;
;     const int total = 24 * 192;
;     int it = lbid();
;     ...
;     if (it < total) ATT_LOAD(it);
;     for (; it < total; it += G_) {
;         const AttnGeom G = attn_geom(it);
; #pragma unroll
;         for (int i = 0; i < 5; ++i) { const int e = tid + 512 * i, kk = e >> 3, c8 = e & 7;
;             if (e < 2176) {
;                 if (kk < 256) *(u32x4*)(Ks + kk * 72 + c8 * 8) = kreg[i];
; #pragma unroll
;                 for (int j = 0; j < 8; ++j) Vt[(c8 * 8 + j) * 320 + (kk ^ (c8 << 3))] = (bf16_t)((vreg[i][j >> 1] >> ((j & 1) * 16)) & 0xffffu); } }
;         const bf16x8 aq0 = q0r, aq1 = q1r;
;         __syncthreads();
;         if (it + G_ < total) ATT_LOAD(it + G_);
;         asm volatile("" ::: "memory");
;         const float* bs = BT + G.hd * 132;
;         f32x4 s[9];
; #pragma unroll
;         for (int kt = 0; kt < 9; ++kt) { const bf16_t* kr = Ks + (16 * w + 16 * kt + fr) * 72 + fq * 8;
;             f32x4 a = (f32x4){0.f, 0.f, 0.f, 0.f};
;             a = __builtin_amdgcn_mfma_f32_16x16x32_bf16(aq0, *(const bf16x8*)kr, a, 0, 0, 0);
;             a = __builtin_amdgcn_mfma_f32_16x16x32_bf16(aq1, *(const bf16x8*)(kr + 32), a, 0, 0, 0); s[kt] = a; }
;         float mx[4], ls[4];
; #pragma unroll
;         for (int i = 0; i < 4; ++i) { const int qi = fq * 4 + i; float m = -3.0e38f;
; #pragma unroll
;             for (int kt = 0; kt < 9; ++kt) { const int rel = 16 * kt + fr - 64 - qi, klat = G.q0 - 64 + 16 * w + 16 * kt + fr;
;                 const bool ok = rel >= -64 && rel <= 64 && klat >= 0 && klat < G.n_lat; const int bi = min(max(rel + 64, 0), 128);
;                 const float v = ok ? s[kt][i] + bs[bi] : -1.0e30f; s[kt][i] = v; m = fmaxf(m, v); }
;             m = fmaxf(m, __shfl_xor(m, 1)); m = fmaxf(m, __shfl_xor(m, 2)); m = fmaxf(m, __shfl_xor(m, 4)); m = fmaxf(m, __shfl_xor(m, 8));
;             float sum = 0.f;
; #pragma unroll
;             for (int kt = 0; kt < 9; ++kt) { const float pv = __expf(s[kt][i] - m); s[kt][i] = pv; sum += pv; }
.LBB0_338:
	v_and_b32_e32 v2, 63, v130
	s_movk_i32 s22, 0xc00
	s_andn2_b64 vcc, exec, s[40:41]
	s_cbranch_vccnz .LBB0_453
	v_and_b32_e32 v0, 48, v130
	v_and_b32_e32 v50, 64, v140
	v_add_u32_e32 v101, 0, v0
	v_xor_b32_e32 v0, 1, v140
	v_add_u32_e32 v50, 64, v50
	v_cmp_lt_i32_e32 vcc, v0, v50
	s_movk_i32 s0, 0x1500
	v_lshlrev_b32_e32 v99, 4, v47
	v_cndmask_b32_e32 v0, v140, v0, vcc
	v_lshlrev_b32_e32 v103, 2, v0
	v_xor_b32_e32 v0, 2, v140
	v_cmp_lt_i32_e32 vcc, v0, v50
	v_and_b32_e32 v92, 56, v48
	v_lshlrev_b32_e32 v51, 4, v46
	v_cndmask_b32_e32 v0, v140, v0, vcc
	v_lshlrev_b32_e32 v104, 2, v0
	v_xor_b32_e32 v0, 4, v140
	v_cmp_lt_i32_e32 vcc, v0, v50
	s_mov_b64 s[86:87], s[90:91]
	v_add_u32_e32 v61, 0x200, v130
	v_cndmask_b32_e32 v0, v140, v0, vcc
	v_lshlrev_b32_e32 v105, 2, v0
	v_xor_b32_e32 v0, 8, v140
	v_cmp_lt_i32_e32 vcc, v0, v50
	v_ashrrev_i32_e32 v110, 3, v61
	s_movk_i32 s1, 0x680
	v_cndmask_b32_e32 v0, v140, v0, vcc
	v_lshlrev_b32_e32 v106, 2, v0
	v_mul_lo_u32 v0, v47, s0
	v_readlane_b32 s0, v254, 9
	v_cmp_gt_i32_e64 s[42:43], s1, v130
	v_add_u32_e32 v63, 0x400, v130
	v_add_u32_e32 v47, s0, v0
	s_movk_i32 s0, 0x880
	v_cmp_gt_i32_e64 s[6:7], s0, v130
	s_movk_i32 s0, 0x100
	v_mul_u32_u24_e32 v0, 0x150, v93
	v_cmp_gt_i32_e64 s[8:9], s0, v98
	v_add3_u32 v107, v47, v0, v51
	v_lshlrev_b32_e32 v0, 1, v92
	v_writelane_b32 v255, s8, 10
	v_lshl_add_u64 v[94:95], s[90:91], 0, v[0:1]
	s_mov_b64 s[90:91], s[6:7]
	v_writelane_b32 v255, s9, 11
	s_and_b64 s[6:7], s[6:7], s[8:9]
	v_writelane_b32 v255, s6, 14
	v_cmp_gt_i32_e64 s[18:19], s0, v110
	v_ashrrev_i32_e32 v111, 3, v63
	v_writelane_b32 v255, s7, 15
	v_writelane_b32 v255, s18, 16
	s_and_b64 s[6:7], s[42:43], s[18:19]
	s_movk_i32 s1, 0x480
	v_writelane_b32 v255, s19, 17
	v_writelane_b32 v255, s6, 18
	v_cmp_gt_i32_e64 s[38:39], s0, v111
	v_cmp_gt_i32_e64 s[46:47], s1, v130
	v_writelane_b32 v255, s7, 19
	v_writelane_b32 v255, s38, 20
	v_add_u32_e32 v65, 0x600, v130
	s_and_b64 s[6:7], s[46:47], s[38:39]
	v_writelane_b32 v255, s39, 21
	v_ashrrev_i32_e32 v112, 3, v65
	v_writelane_b32 v255, s6, 22
	s_movk_i32 s3, 0x280
	v_cmp_gt_i32_e64 s[40:41], s0, v112
	v_writelane_b32 v255, s7, 23
	v_cmp_gt_i32_e64 s[50:51], s3, v130
	v_writelane_b32 v255, s40, 24
	v_add_u32_e32 v67, 0x800, v130
	s_and_b64 s[6:7], s[50:51], s[40:41]
	v_writelane_b32 v255, s41, 25
	v_ashrrev_i32_e32 v113, 3, v67
	s_movk_i32 s1, 0x80
	v_writelane_b32 v255, s6, 26
	v_cmp_gt_i32_e64 s[54:55], s1, v130
	v_cmp_gt_i32_e64 s[0:1], s0, v113
	v_writelane_b32 v255, s7, 27
	v_lshlrev_b32_e32 v48, 2, v46
	v_writelane_b32 v255, s0, 28
	v_sub_u32_e32 v115, v93, v48
	v_add_u32_e32 v76, 0x80, v115
	v_writelane_b32 v255, s1, 29
	s_and_b64 s[0:1], s[54:55], s[0:1]
	v_writelane_b32 v255, s0, 30
	v_or_b32_e32 v77, 2, v48
	v_sub_u32_e32 v118, v93, v77
	v_writelane_b32 v255, s1, 31
	s_movk_i32 s0, 0x81
	v_cmp_gt_u32_e64 s[6:7], s0, v115
	v_add_u32_e32 v119, 0x80, v118
	v_or_b32_e32 v108, v48, v99
	v_writelane_b32 v254, s6, 49
	v_lshl_add_u32 v50, v93, 1, v47
	v_lshlrev_b32_e32 v44, 3, v46
	v_writelane_b32 v254, s7, 50
	v_cmp_gt_u32_e64 s[6:7], s0, v76
	v_or_b32_e32 v76, 1, v48
	v_sub_u32_e32 v116, v93, v76
	v_writelane_b32 v254, s6, 37
	v_add_u32_e32 v117, 0x80, v116
	v_or_b32_e32 v48, 3, v48
	v_writelane_b32 v254, s7, 38
	v_cmp_gt_u32_e64 s[6:7], s0, v116
	v_sub_u32_e32 v120, v93, v48
	v_add_u32_e32 v121, 0x80, v120
	v_writelane_b32 v255, s6, 0
	v_add_u32_e32 v51, v44, v99
	v_mul_u32_u24_e32 v48, 0x540, v46
	v_writelane_b32 v255, s7, 1
	v_cmp_gt_u32_e64 s[6:7], s0, v117
	v_or_b32_e32 v127, 16, v93
	v_bitop3_b32 v78, v51, v127, 24 bitop3:0x78
	v_writelane_b32 v255, s6, 2
	v_or_b32_e32 v129, 32, v93
	v_bitop3_b32 v79, v51, v129, 40 bitop3:0x78
	v_writelane_b32 v255, s7, 3
	v_cmp_gt_u32_e64 s[6:7], s0, v118
	v_or_b32_e32 v132, 48, v93
	v_bitop3_b32 v80, v51, v132, 56 bitop3:0x78
	v_writelane_b32 v255, s6, 4
	v_and_b32_e32 v3, 7, v130
	v_lshlrev_b32_e32 v49, 3, v3
	v_writelane_b32 v255, s7, 5
	v_cmp_gt_u32_e64 s[6:7], s0, v119
	v_or_b32_e32 v100, v99, v93
	v_lshrrev_b32_e32 v109, 3, v2
	v_writelane_b32 v255, s6, 6
	s_movk_i32 s2, 0x90
	v_xor_b32_e32 v60, v49, v98
	v_writelane_b32 v255, s7, 7
; __device__ void attn_items(const Params& p, unsigned char* shm) {
;     ...
;         for (int i = 0; i < 5; ++i) { const int e = tid + 512 * i, kk = e >> 3, c8 = e & 7;
;             if (e < 2176) {
;                 if (kk < 256) *(u32x4*)(Ks + kk * 72 + c8 * 8) = kreg[i];
; #pragma unroll
;                 for (int j = 0; j < 8; ++j) Vt[(c8 * 8 + j) * 320 + (kk ^ (c8 << 3))] = (bf16_t)((vreg[i][j >> 1] >> ((j & 1) * 16)) & 0xffffu); } }
;         const bf16x8 aq0 = q0r, aq1 = q1r;
;         __syncthreads();
;         if (it + G_ < total) ATT_LOAD(it + G_);
;         asm volatile("" ::: "memory");
;         const float* bs = BT + G.hd * 132;
;         f32x4 s[9];
; #pragma unroll
;         for (int kt = 0; kt < 9; ++kt) { const bf16_t* kr = Ks + (16 * w + 16 * kt + fr) * 72 + fq * 8;
;             f32x4 a = (f32x4){0.f, 0.f, 0.f, 0.f};
;             a = __builtin_amdgcn_mfma_f32_16x16x32_bf16(aq0, *(const bf16x8*)kr, a, 0, 0, 0);
;             a = __builtin_amdgcn_mfma_f32_16x16x32_bf16(aq1, *(const bf16x8*)(kr + 32), a, 0, 0, 0); s[kt] = a; }
;         float mx[4], ls[4];
; #pragma unroll
;         for (int i = 0; i < 4; ++i) { const int qi = fq * 4 + i; float m = -3.0e38f;
; #pragma unroll
;             for (int kt = 0; kt < 9; ++kt) { const int rel = 16 * kt + fr - 64 - qi, klat = G.q0 - 64 + 16 * w + 16 * kt + fr;
;                 const bool ok = rel >= -64 && rel <= 64 && klat >= 0 && klat < G.n_lat; const int bi = min(max(rel + 64, 0), 128);
;                 const float v = ok ? s[kt][i] + bs[bi] : -1.0e30f; s[kt][i] = v; m = fmaxf(m, v); }
;             m = fmaxf(m, __shfl_xor(m, 1)); m = fmaxf(m, __shfl_xor(m, 2)); m = fmaxf(m, __shfl_xor(m, 4)); m = fmaxf(m, __shfl_xor(m, 8));
;             float sum = 0.f;
; #pragma unroll
;             for (int kt = 0; kt < 9; ++kt) { const float pv = __expf(s[kt][i] - m); s[kt][i] = pv; sum += pv; }
;             sum += __shfl_xor(sum, 1); sum += __shfl_xor(sum, 2); sum += __shfl_xor(sum, 4); sum += __shfl_xor(sum, 8);
;             mx[i] = m; ls[i] = sum; }
;         bf16_t* Pw = Ps + w * 16 * 168;
; #pragma unroll
;         for (int i = 0; i < 4; ++i) {
; #pragma unroll
;             for (int kt = 0; kt < 9; ++kt) Pw[(fq * 4 + i) * 168 + 16 * kt + fr] = f2bf(s[kt][i]);
;             Pw[(fq * 4 + i) * 168 + 144 + fr] = 0; }
;         __syncthreads();
;         f32x4 o[4];
; #pragma unroll
	v_cmp_gt_u32_e64 s[6:7], s0, v120
	v_cmp_gt_u32_e64 s[0:1], s0, v121
	v_xor_b32_e32 v62, v110, v49
	v_writelane_b32 v255, s6, 12
	v_xor_b32_e32 v64, v111, v49
	v_xor_b32_e32 v66, v112, v49
	v_writelane_b32 v255, s7, 13
	v_writelane_b32 v255, s0, 8
	v_xor_b32_e32 v49, v113, v49
	v_mul_lo_u32 v114, v100, s2
	v_writelane_b32 v255, s1, 9
	s_movk_i32 s0, 0x540
	v_mad_u32_u24 v122, v46, s0, v50
	s_movk_i32 s0, 0x150
	v_mad_u32_u24 v77, v76, s0, s0
	v_add_u32_e32 v124, v50, v77
	v_mov_b32_e32 v77, 0x2a0
	v_mul_u32_u24_e32 v46, 0x150, v76
	v_mad_u32_u24 v123, v76, s0, v50
	v_mad_u32_u24 v76, v76, s0, v77
	v_add_u32_e32 v125, v50, v76
	v_mad_u32_u24 v76, v93, s3, 0
	v_bitop3_b32 v77, v51, v130, 8 bitop3:0x78
	v_lshl_add_u32 v126, v77, 1, v76
	v_add_u32_e32 v77, 0x2800, v76
	v_lshl_add_u32 v128, v78, 1, v77
	v_add_u32_e32 v78, 0x5000, v76
	v_lshl_add_u32 v131, v79, 1, v78
	v_add_u32_e32 v79, 0x7800, v76
	v_lshl_add_u32 v133, v80, 1, v79
	v_add_u32_e32 v80, 32, v51
	v_bitop3_b32 v81, v80, v130, 8 bitop3:0x78
	v_lshl_add_u32 v134, v81, 1, v76
	v_bitop3_b32 v81, v80, v127, 24 bitop3:0x78
	v_lshl_add_u32 v135, v81, 1, v77
	v_bitop3_b32 v81, v80, v129, 40 bitop3:0x78
	v_bitop3_b32 v80, v80, v132, 56 bitop3:0x78
	v_lshl_add_u32 v137, v80, 1, v79
	v_add_u32_e32 v80, 64, v51
	v_lshl_add_u32 v136, v81, 1, v78
	v_bitop3_b32 v81, v80, v130, 8 bitop3:0x78
	v_lshl_add_u32 v138, v81, 1, v76
	v_bitop3_b32 v81, v80, v127, 24 bitop3:0x78
	v_lshl_add_u32 v139, v81, 1, v77
	v_bitop3_b32 v81, v80, v129, 40 bitop3:0x78
	v_bitop3_b32 v80, v80, v132, 56 bitop3:0x78
	v_lshl_add_u32 v141, v80, 1, v79
	v_add_u32_e32 v80, 0x60, v51
	v_lshl_add_u32 v140, v81, 1, v78
	v_bitop3_b32 v81, v80, v130, 8 bitop3:0x78
	v_lshl_add_u32 v142, v81, 1, v76
	v_bitop3_b32 v81, v80, v127, 24 bitop3:0x78
	v_lshl_add_u32 v143, v81, 1, v77
	v_bitop3_b32 v81, v80, v129, 40 bitop3:0x78
	v_bitop3_b32 v80, v80, v132, 56 bitop3:0x78
	v_add_u32_e32 v51, 0x80, v51
	v_lshl_add_u32 v145, v80, 1, v79
	v_bitop3_b32 v80, v51, v130, 8 bitop3:0x78
	v_lshl_add_u32 v130, v80, 1, v76
	v_bitop3_b32 v76, v51, v127, 24 bitop3:0x78
	v_lshl_add_u32 v146, v76, 1, v77
	v_bitop3_b32 v76, v51, v129, 40 bitop3:0x78
	v_bitop3_b32 v51, v51, v132, 56 bitop3:0x78
	v_or_b32_e32 v149, 8, v109
	v_lshl_add_u32 v45, v3, 4, 0
	v_add_u32_e32 v47, v47, v0
	v_mul_u32_u24_e32 v0, 0x150, v109
	v_mul_lo_u32 v2, v98, s2
	v_lshl_add_u32 v60, v60, 1, 0
	v_mul_u32_u24_e32 v3, 0x1400, v3
	v_mul_lo_u32 v61, v110, s2
	v_lshl_add_u32 v62, v62, 1, 0
	v_mul_lo_u32 v63, v111, s2
	v_lshl_add_u32 v64, v64, 1, 0
	v_mul_lo_u32 v65, v112, s2
	v_lshl_add_u32 v66, v66, 1, 0
	v_mul_lo_u32 v67, v113, s2
	v_lshl_add_u32 v49, v49, 1, 0
	v_add_u32_e32 v68, 0x900, v114
	v_add_u32_e32 v69, 0x1200, v114
	v_add_u32_e32 v70, 0x1b00, v114
	v_add_u32_e32 v71, 0x2400, v114
	v_add_u32_e32 v72, 0x2d00, v114
	v_add_u32_e32 v73, 0x3600, v114
	v_add_u32_e32 v74, 0x3f00, v114
	v_add_u32_e32 v75, 0x4800, v114
	v_lshl_add_u32 v148, v51, 1, v79
	v_mul_u32_u24_e32 v51, 0x150, v149
	v_readlane_b32 s0, v251, 10
	s_movk_i32 s23, 0xff7f
	v_subrev_u32_e32 v102, 64, v99
	v_cmp_eq_u32_e64 s[36:37], 0, v93
	v_lshl_add_u32 v144, v81, 1, v78
	v_lshl_add_u32 v147, v76, 1, v78
	v_or_b32_e32 v150, 0x50, v93
	v_or_b32_e32 v151, 0x60, v93
	v_or_b32_e32 v152, 0x70, v93
	v_or_b32_e32 v153, 0x80, v93
	s_lshl_b32 s2, s4, 7
	s_movk_i32 s3, 0x80
	v_add_u32_e32 v154, v45, v2
	v_add_u32_e32 v155, v60, v3
	v_add_u32_e32 v156, v45, v61
	v_add_u32_e32 v157, v62, v3
	v_add_u32_e32 v158, v45, v63
	v_add_u32_e32 v159, v64, v3
	v_add_u32_e32 v160, v45, v65
	v_add_u32_e32 v161, v66, v3
	v_add_u32_e32 v162, v45, v67
	v_add_u32_e32 v163, v49, v3
	v_lshlrev_b32_e32 v96, 1, v44
	v_add_u32_e32 v164, v101, v68
	v_add_u32_e32 v165, v101, v69
	v_add_u32_e32 v166, v101, v70
	v_add_u32_e32 v167, v101, v71
	v_add_u32_e32 v168, v101, v72
	v_add_u32_e32 v169, v101, v73
	v_add_u32_e32 v170, v101, v74
	v_add_u32_e32 v171, v101, v75
	v_add_u32_e32 v172, v50, v48
	v_add_u32_e32 v173, v47, v0
	v_add_u32_e32 v174, v47, v51
	v_add_u32_e32 v175, v50, v46
	v_readlane_b32 s1, v251, 11
	v_readfirstlane_b32 s0, v229
	s_lshr_b32 s0, s0, 6
	s_cmp_ge_u32 s0, 4
	s_cbranch_scc1 .Lprio_skip3
	s_setprio 1
